# final combine+LN phase software-pipelined over rows: next row's state row, expert rows, tail ids and statistics in flight while the current row is normalised
# speedup vs baseline: 1.0101x; 1.0034x over previous
; template <int SRC, int EXTRA, bool OUT8 = false> ...
;     ...
;     f32x4 gv[4], bv[4];
; #pragma unroll
;     for (int j = 0; j < 4; ++j) { gv[j] = *(const f32x4*)(g + 256 * j + 4 * lane); bv[j] = *(const f32x4*)(b + 256 * j + 4 * lane); }
;     const int gw = blockIdx.x * NWAVES + wave, NGW = G * NWAVES;
;     for (int row = gw; row < M; row += NGW) {
;         f32x4 v[4];
;         if (SRC == 0) {
; #pragma unroll
;             for (int j = 0; j < 4; ++j) v[j] = *(const f32x4*)(src + (size_t)row * 1024 + 256 * j + 4 * lane);
;         } else {
;             const int p0 = pos[2 * row], p1 = pos[2 * row + 1]; const float w0 = gwt[2 * row], w1 = gwt[2 * row + 1]; const float hm = hp.stats[2 * row], hr = hp.stats[2 * row + 1];
; #pragma unroll
;             for (int j = 0; j < 4; ++j) { const f32x4 a = (*(const f32x4*)(hp.src + (size_t)row * 1024 + 256 * j + 4 * lane) - hm) * hr * *(const f32x4*)(hp.g + 256 * j + 4 * lane) + *(const f32x4*)(hp.b + 256 * j + 4 * lane);
;                 f32x4 y[2];
; #pragma unroll
;                 for (int q = 0; q < 2; ++q) { const int p = q ? p1 : p0; const int t = __builtin_amdgcn_readfirstlane(tailid[(p >> 8) * 4 + j]);
;                     if (t < 0) y[q] = *(const f32x4*)(ys + (size_t)p * 1024 + 256 * j + 4 * lane);
;                     else { f32x4 acc = (f32x4){0.f, 0.f, 0.f, 0.f};
; #pragma unroll
;                         for (int sl = 0; sl < 7; ++sl) acc = acc + *(const f32x4*)(part + ((size_t)(t * 7 + sl) * 256 + (p & 255)) * 256 + 4 * lane);
;                         y[q] = acc; } }
;                 v[j] = a * ALPHA + y[0] * w0 + y[1] * w1; }
.LBB0_2243:
	s_or_b64 exec, exec, s[6:7]
	s_mov_b64 s[12:13], s[0:1]
	s_mov_b64 s[18:19], s[0:1]
	s_mov_b64 s[8:9], s[0:1]
	s_mov_b64 s[6:7], s[0:1]
	s_mov_b64 s[10:11], s[0:1]
	s_mov_b64 s[16:17], s[0:1]
	s_mov_b64 s[20:21], s[0:1]
	s_mov_b64 s[22:23], s[0:1]
	s_mov_b64 s[14:15], s[0:1]
	s_mov_b64 s[24:25], s[0:1]
	s_mov_b64 s[26:27], s[0:1]
	s_and_b64 vcc, exec, s[4:5]
	s_waitcnt lgkmcnt(0)
	s_barrier
	v_mbcnt_lo_u32_b32 v32, -1, 0
	v_mbcnt_hi_u32_b32 v32, -1, v32
	s_cbranch_vccnz .LBB0_2280
	s_load_dwordx2 s[4:5], s[24:25], 0xa8
	s_load_dwordx2 s[28:29], s[26:27], 0xb0
	v_lshlrev_b32_e32 v0, 4, v32
	v_mov_b32_e32 v113, 0
	v_and_b32_e32 v112, 0x3f0, v0
	s_waitcnt lgkmcnt(0)
	v_lshl_add_u64 v[0:1], s[4:5], 0, v[112:113]
	s_mov_b64 s[4:5], 0x1000
	s_movk_i32 s3, 0x1000
	v_lshl_add_u64 v[34:35], v[0:1], 0, s[4:5]
	v_add_co_u32_e32 v0, vcc, s3, v0
	v_lshl_add_u64 v[4:5], s[28:29], 0, v[112:113]
	s_nop 0
	v_addc_co_u32_e32 v1, vcc, 0, v1, vcc
	v_add_co_u32_e32 v38, vcc, s3, v4
	v_lshl_add_u64 v[36:37], v[4:5], 0, s[4:5]
	s_nop 0
	v_addc_co_u32_e32 v39, vcc, 0, v5, vcc
	global_load_dwordx4 v[0:3], v[0:1], off
	s_nop 0
	global_load_dwordx4 v[4:7], v[38:39], off
	global_load_dwordx4 v[8:11], v[34:35], off offset:1024
	global_load_dwordx4 v[12:15], v[34:35], off offset:2048
	global_load_dwordx4 v[16:19], v[36:37], off offset:1024
	global_load_dwordx4 v[20:23], v[36:37], off offset:2048
	global_load_dwordx4 v[24:27], v[34:35], off offset:3072
	global_load_dwordx4 v[28:31], v[36:37], off offset:3072
	s_load_dwordx2 s[24:25], s[18:19], 0xc0
	s_load_dwordx2 s[38:39], s[12:13], 0xc0
	s_nop 0
	s_load_dwordx2 s[12:13], s[8:9], 0x68
	s_load_dwordx2 s[18:19], s[16:17], 0xc0
	s_load_dwordx2 s[40:41], s[6:7], 0x70
	s_load_dwordx2 s[28:29], s[20:21], 0xc0
	s_load_dwordx2 s[42:43], s[10:11], 0xc0
	s_load_dwordx2 s[36:37], s[22:23], 0xc0
	s_nop 0
	s_load_dwordx2 s[6:7], s[14:15], 0xc0
	s_load_dwordx2 s[16:17], s[0:1], 0xb8
	s_waitcnt lgkmcnt(0)
	v_lshl_add_u64 v[34:35], s[12:13], 0, v[112:113]
	s_add_u32 s24, s24, 0x400000
	s_addc_u32 s25, s25, 0
	s_add_u32 s26, s18, 0x380000
	s_addc_u32 s27, s19, 0
	s_add_u32 s28, s28, 0x340000
	s_addc_u32 s29, s29, 0
	s_add_u32 s36, s36, 0x3c8000
	v_lshl_add_u64 v[114:115], v[34:35], 0, s[4:5]
	v_lshl_add_u64 v[34:35], s[40:41], 0, v[112:113]
	s_addc_u32 s37, s37, 0
	v_lshl_add_u64 v[116:117], v[34:35], 0, s[4:5]
	v_lshl_add_u64 v[34:35], s[6:7], 0, v[112:113]
	s_mov_b64 s[0:1], 0xe500000
	v_lshl_add_u64 v[118:119], v[34:35], 0, s[0:1]
	v_lshl_add_u64 v[34:35], s[42:43], 0, v[112:113]
	s_mov_b64 s[0:1], 0x2c500000
	s_cmp_lg_u64 s[16:17], 0
	v_lshl_add_u64 v[120:121], v[34:35], 0, s[0:1]
	s_cselect_b64 s[4:5], -1, 0
	s_lshl_b32 s0, s2, 4
	s_lshl_b32 s1, s68, 1
	s_ashr_i32 s35, s34, 31
	s_add_i32 s6, s0, s1
	s_lshl_b32 s15, s33, 4
	s_lshl_b64 s[0:1], s[34:35], 12
	s_add_u32 s8, s38, s0
	s_addc_u32 s9, s39, s1
	s_ashr_i32 s31, s30, 31
	s_lshl_b64 s[10:11], s[30:31], 12
	v_and_b32_e32 v32, 63, v32
	s_add_u32 s12, s16, s0
	s_mov_b32 s3, 0
	v_lshlrev_b32_e32 v112, 4, v32
	s_addc_u32 s13, s17, s1
	s_mov_b32 s31, 0x28500000
	s_mov_b32 s14, 0x3fb504f3
	v_mov_b32_e32 v126, 0x3727c5ac
	s_mov_b32 s33, 0xf800000
	v_mov_b32_e32 v127, 0x260
	s_ashr_i32 s7, s6, 31
	s_lshl_b64 s[0:1], s[6:7], 2
	s_add_u32 s16, s26, s0
	s_addc_u32 s17, s27, s1
	global_load_dwordx2 v[158:159], v113, s[16:17]
	s_waitcnt vmcnt(0)
	v_readfirstlane_b32 s52, v158
	v_readfirstlane_b32 s53, v159
	s_add_i32 s54, s34, s30
	s_cmpk_lt_i32 s54, 0x4000
	s_cselect_b32 s55, s15, 0
	s_mov_b32 s0, s6
	s_ashr_i32 s1, s0, 31
	s_lshl_b64 s[0:1], s[0:1], 2
	s_add_u32 s18, s24, s0
	s_addc_u32 s19, s25, s1
	global_load_dwordx2 v[198:199], v113, s[18:19]
	s_add_u32 s18, s28, s0
	s_addc_u32 s19, s29, s1
	global_load_dwordx2 v[166:167], v113, s[18:19]
	s_ashr_i32 s0, s52, 6
	s_and_b32 s0, s0, -4
	s_ashr_i32 s1, s0, 31
	s_lshl_b64 s[0:1], s[0:1], 2
	s_add_u32 s18, s36, s0
	s_addc_u32 s19, s37, s1
	global_load_dwordx4 v[250:253], v113, s[18:19]
	s_ashr_i32 s0, s53, 6
	s_and_b32 s0, s0, -4
	s_ashr_i32 s1, s0, 31
	s_lshl_b64 s[0:1], s[0:1], 2
	s_add_u32 s18, s36, s0
	s_addc_u32 s19, s37, s1
	global_load_dwordx4 v[194:197], v113, s[18:19]
	s_ashr_i32 s1, s52, 31
	s_mov_b32 s0, s52
	s_lshl_b64 s[0:1], s[0:1], 12
	v_lshl_add_u64 v[162:163], v[120:121], 0, s[0:1]
	global_load_dwordx4 v[218:221], v[162:163], off
	global_load_dwordx4 v[222:225], v[162:163], off offset:1024
	global_load_dwordx4 v[226:229], v[162:163], off offset:2048
	global_load_dwordx4 v[230:233], v[162:163], off offset:3072
	s_ashr_i32 s1, s53, 31
	s_mov_b32 s0, s53
	s_lshl_b64 s[0:1], s[0:1], 12
	v_lshl_add_u64 v[162:163], v[120:121], 0, s[0:1]
	global_load_dwordx4 v[234:237], v[162:163], off
	global_load_dwordx4 v[238:241], v[162:163], off offset:1024
	global_load_dwordx4 v[242:245], v[162:163], off offset:2048
	global_load_dwordx4 v[246:249], v[162:163], off offset:3072
	v_lshl_add_u64 v[160:161], s[8:9], 0, v[112:113]
	v_add_co_u32_e32 v160, vcc, s31, v160
	s_nop 1
	v_addc_co_u32_e32 v161, vcc, 0, v161, vcc
	global_load_dwordx4 v[202:205], v[160:161], off
	global_load_dwordx4 v[206:209], v[160:161], off offset:1024
	global_load_dwordx4 v[210:213], v[160:161], off offset:2048
	global_load_dwordx4 v[214:217], v[160:161], off offset:3072
	s_add_i32 s0, s6, s55
	s_ashr_i32 s1, s0, 31
	s_lshl_b64 s[0:1], s[0:1], 2
	s_add_u32 s18, s26, s0
	s_addc_u32 s19, s27, s1
	global_load_dwordx2 v[158:159], v113, s[18:19]
	s_waitcnt vmcnt(0)
	s_branch .LBB0_2246

; template <int SRC, int EXTRA, bool OUT8 = false> ...
;     ...
;             const int p0 = pos[2 * row], p1 = pos[2 * row + 1]; const float w0 = gwt[2 * row], w1 = gwt[2 * row + 1]; const float hm = hp.stats[2 * row], hr = hp.stats[2 * row + 1];
; #pragma unroll
;             for (int j = 0; j < 4; ++j) { const f32x4 a = (*(const f32x4*)(hp.src + (size_t)row * 1024 + 256 * j + 4 * lane) - hm) * hr * *(const f32x4*)(hp.g + 256 * j + 4 * lane) + *(const f32x4*)(hp.b + 256 * j + 4 * lane);
;                 f32x4 y[2];
; #pragma unroll
;                 for (int q = 0; q < 2; ++q) { const int p = q ? p1 : p0; const int t = __builtin_amdgcn_readfirstlane(tailid[(p >> 8) * 4 + j]);
;                     if (t < 0) y[q] = *(const f32x4*)(ys + (size_t)p * 1024 + 256 * j + 4 * lane);
;                     else { f32x4 acc = (f32x4){0.f, 0.f, 0.f, 0.f};
; #pragma unroll
;                         for (int sl = 0; sl < 7; ++sl) acc = acc + *(const f32x4*)(part + ((size_t)(t * 7 + sl) * 256 + (p & 255)) * 256 + 4 * lane);
;                         y[q] = acc; } }
;                 v[j] = a * ALPHA + y[0] * w0 + y[1] * w1; }
.LBB0_2246:
	s_waitcnt vmcnt(4)
	v_mov_b64_e32 v[156:157], v[158:159]
	v_mov_b64_e32 v[40:41], v[202:203]
	v_mov_b64_e32 v[42:43], v[204:205]
	v_mov_b64_e32 v[44:45], v[218:219]
	v_mov_b64_e32 v[46:47], v[220:221]
	v_mov_b64_e32 v[48:49], v[234:235]
	v_mov_b64_e32 v[50:51], v[236:237]
	v_mov_b64_e32 v[60:61], v[206:207]
	v_mov_b64_e32 v[62:63], v[208:209]
	v_mov_b64_e32 v[64:65], v[222:223]
	v_mov_b64_e32 v[66:67], v[224:225]
	v_mov_b64_e32 v[68:69], v[238:239]
	v_mov_b64_e32 v[70:71], v[240:241]
	v_mov_b64_e32 v[80:81], v[210:211]
	v_mov_b64_e32 v[82:83], v[212:213]
	v_mov_b64_e32 v[84:85], v[226:227]
	v_mov_b64_e32 v[86:87], v[228:229]
	v_mov_b64_e32 v[96:97], v[242:243]
	v_mov_b64_e32 v[98:99], v[244:245]
	v_mov_b64_e32 v[100:101], v[214:215]
	v_mov_b64_e32 v[102:103], v[216:217]
	v_mov_b64_e32 v[104:105], v[230:231]
	v_mov_b64_e32 v[106:107], v[232:233]
	v_mov_b64_e32 v[108:109], v[246:247]
	v_mov_b64_e32 v[110:111], v[248:249]
	v_mov_b64_e32 v[168:169], v[250:251]
	v_mov_b64_e32 v[170:171], v[252:253]
	v_mov_b64_e32 v[172:173], v[194:195]
	v_mov_b64_e32 v[174:175], v[196:197]
	v_mov_b64_e32 v[124:125], v[198:199]
	v_mov_b64_e32 v[122:123], v[166:167]
	s_mov_b32 s16, s52
	s_mov_b32 s22, s53
	v_readfirstlane_b32 s52, v156
	v_readfirstlane_b32 s53, v157
	v_and_b32_e32 v176, v168, v169
	v_and_b32_e32 v177, v170, v171
	v_and_b32_e32 v178, v172, v173
	v_and_b32_e32 v179, v174, v175
	v_and_b32_e32 v176, v176, v177
	v_and_b32_e32 v178, v178, v179
	v_and_b32_e32 v176, v176, v178
	s_nop 0
	v_readfirstlane_b32 s0, v176
	s_cmp_lt_i32 s0, 0
	s_cbranch_scc1 .Lcomb_nosplit
	v_readfirstlane_b32 s1, v168
	s_cmp_lt_i32 s1, 0
	s_cbranch_scc1 .Lcomb_n00
	s_mul_i32 s20, s1, 7
	s_lshl_b32 s1, s16, 10
	s_and_b32 s2, s1, 0x3fc00
	s_mov_b32 s21, s3
	v_lshl_add_u64 v[176:177], v[118:119], 0, s[2:3]
	s_lshl_b64 s[38:39], s[20:21], 18
	v_lshl_add_u64 v[178:179], v[176:177], 0, s[38:39]
	global_load_dwordx4 v[128:131], v[178:179], off
	s_add_i32 s2, s20, 1
	s_lshl_b64 s[38:39], s[2:3], 18
	v_lshl_add_u64 v[182:183], v[176:177], 0, s[38:39]
	global_load_dwordx4 v[132:135], v[182:183], off
	s_add_i32 s2, s20, 2
	s_lshl_b64 s[38:39], s[2:3], 18
	v_lshl_add_u64 v[184:185], v[176:177], 0, s[38:39]
	global_load_dwordx4 v[136:139], v[184:185], off
	s_add_i32 s2, s20, 3
	s_lshl_b64 s[38:39], s[2:3], 18
	v_lshl_add_u64 v[186:187], v[176:177], 0, s[38:39]
	global_load_dwordx4 v[140:143], v[186:187], off
	s_add_i32 s2, s20, 4
	s_lshl_b64 s[38:39], s[2:3], 18
	v_lshl_add_u64 v[188:189], v[176:177], 0, s[38:39]
	global_load_dwordx4 v[144:147], v[188:189], off
	s_add_i32 s2, s20, 5
	s_lshl_b64 s[38:39], s[2:3], 18
	v_lshl_add_u64 v[190:191], v[176:177], 0, s[38:39]
	global_load_dwordx4 v[148:151], v[190:191], off
	s_add_i32 s2, s20, 6
	s_lshl_b64 s[38:39], s[2:3], 18
	v_lshl_add_u64 v[192:193], v[176:177], 0, s[38:39]
	global_load_dwordx4 v[152:155], v[192:193], off
	s_waitcnt vmcnt(6)
	v_pk_add_f32 v[46:47], v[130:131], 0 op_sel_hi:[1,0]
	v_pk_add_f32 v[44:45], v[128:129], 0 op_sel_hi:[1,0]
	s_waitcnt vmcnt(5)
	v_pk_add_f32 v[46:47], v[46:47], v[134:135]
	v_pk_add_f32 v[44:45], v[44:45], v[132:133]
	s_waitcnt vmcnt(4)
	v_pk_add_f32 v[46:47], v[46:47], v[138:139]
	v_pk_add_f32 v[44:45], v[44:45], v[136:137]
	s_waitcnt vmcnt(3)
	v_pk_add_f32 v[46:47], v[46:47], v[142:143]
	v_pk_add_f32 v[44:45], v[44:45], v[140:141]
	s_waitcnt vmcnt(2)
	v_pk_add_f32 v[46:47], v[46:47], v[146:147]
	v_pk_add_f32 v[44:45], v[44:45], v[144:145]
	s_waitcnt vmcnt(1)
	v_pk_add_f32 v[46:47], v[46:47], v[150:151]
	v_pk_add_f32 v[44:45], v[44:45], v[148:149]
	s_waitcnt vmcnt(0)
	v_pk_add_f32 v[46:47], v[46:47], v[154:155]
	v_pk_add_f32 v[44:45], v[44:45], v[152:153]

; template <int SRC, int EXTRA, bool OUT8 = false> ...
;     ...
;             const int p0 = pos[2 * row], p1 = pos[2 * row + 1]; const float w0 = gwt[2 * row], w1 = gwt[2 * row + 1]; const float hm = hp.stats[2 * row], hr = hp.stats[2 * row + 1];
; #pragma unroll
;             for (int j = 0; j < 4; ++j) { const f32x4 a = (*(const f32x4*)(hp.src + (size_t)row * 1024 + 256 * j + 4 * lane) - hm) * hr * *(const f32x4*)(hp.g + 256 * j + 4 * lane) + *(const f32x4*)(hp.b + 256 * j + 4 * lane);
;                 f32x4 y[2];
; #pragma unroll
;                 for (int q = 0; q < 2; ++q) { const int p = q ? p1 : p0; const int t = __builtin_amdgcn_readfirstlane(tailid[(p >> 8) * 4 + j]);
;                     if (t < 0) y[q] = *(const f32x4*)(ys + (size_t)p * 1024 + 256 * j + 4 * lane);
;                     else { f32x4 acc = (f32x4){0.f, 0.f, 0.f, 0.f};
; #pragma unroll
;                         for (int sl = 0; sl < 7; ++sl) acc = acc + *(const f32x4*)(part + ((size_t)(t * 7 + sl) * 256 + (p & 255)) * 256 + 4 * lane);
;                         y[q] = acc; } }
;                 v[j] = a * ALPHA + y[0] * w0 + y[1] * w1; }
.Lcomb_n13:
.Lcomb_nosplit:
	global_load_dwordx4 v[32:35], v[114:115], off
	global_load_dwordx4 v[52:55], v[114:115], off offset:1024
	global_load_dwordx4 v[72:75], v[114:115], off offset:2048
	global_load_dwordx4 v[88:91], v[114:115], off offset:3072
	global_load_dwordx4 v[36:39], v[116:117], off
	global_load_dwordx4 v[56:59], v[116:117], off offset:1024
	global_load_dwordx4 v[76:79], v[116:117], off offset:2048
	global_load_dwordx4 v[92:95], v[116:117], off offset:3072
	s_lshl_b32 s58, s15, 1
	s_add_i32 s54, s34, s30
	s_cmpk_lt_i32 s54, 0x4000
	s_cselect_b32 s55, s15, 0
	s_cselect_b32 s56, s10, 0
	s_cselect_b32 s57, s11, 0
	s_add_i32 s54, s54, s30
	s_cmpk_lt_i32 s54, 0x4000
	s_cselect_b32 s58, s58, s55
	s_add_i32 s0, s6, s55
	s_ashr_i32 s1, s0, 31
	s_lshl_b64 s[0:1], s[0:1], 2
	s_add_u32 s18, s24, s0
	s_addc_u32 s19, s25, s1
	global_load_dwordx2 v[198:199], v113, s[18:19]
	s_add_u32 s18, s28, s0
	s_addc_u32 s19, s29, s1
	global_load_dwordx2 v[166:167], v113, s[18:19]
	s_ashr_i32 s0, s52, 6
	s_and_b32 s0, s0, -4
	s_ashr_i32 s1, s0, 31
	s_lshl_b64 s[0:1], s[0:1], 2
	s_add_u32 s18, s36, s0
	s_addc_u32 s19, s37, s1
	global_load_dwordx4 v[250:253], v113, s[18:19]
	s_ashr_i32 s0, s53, 6
	s_and_b32 s0, s0, -4
	s_ashr_i32 s1, s0, 31
	s_lshl_b64 s[0:1], s[0:1], 2
	s_add_u32 s18, s36, s0
	s_addc_u32 s19, s37, s1
	global_load_dwordx4 v[194:197], v113, s[18:19]
	s_ashr_i32 s1, s52, 31
	s_mov_b32 s0, s52
	s_lshl_b64 s[0:1], s[0:1], 12
	v_lshl_add_u64 v[162:163], v[120:121], 0, s[0:1]
	global_load_dwordx4 v[218:221], v[162:163], off
	global_load_dwordx4 v[222:225], v[162:163], off offset:1024
	global_load_dwordx4 v[226:229], v[162:163], off offset:2048
	global_load_dwordx4 v[230:233], v[162:163], off offset:3072
	s_ashr_i32 s1, s53, 31
	s_mov_b32 s0, s53
	s_lshl_b64 s[0:1], s[0:1], 12
	v_lshl_add_u64 v[162:163], v[120:121], 0, s[0:1]
	global_load_dwordx4 v[234:237], v[162:163], off
	global_load_dwordx4 v[238:241], v[162:163], off offset:1024
	global_load_dwordx4 v[242:245], v[162:163], off offset:2048
	global_load_dwordx4 v[246:249], v[162:163], off offset:3072
	v_lshl_add_u64 v[160:161], s[8:9], 0, v[112:113]
	v_lshl_add_u64 v[160:161], v[160:161], 0, s[56:57]
	v_add_co_u32_e32 v160, vcc, s31, v160
	s_nop 1
	v_addc_co_u32_e32 v161, vcc, 0, v161, vcc
	global_load_dwordx4 v[202:205], v[160:161], off
	global_load_dwordx4 v[206:209], v[160:161], off offset:1024
	global_load_dwordx4 v[210:213], v[160:161], off offset:2048
	global_load_dwordx4 v[214:217], v[160:161], off offset:3072
	s_add_i32 s0, s6, s58
	s_ashr_i32 s1, s0, 31
	s_lshl_b64 s[0:1], s[0:1], 2
	s_add_u32 s18, s26, s0
	s_addc_u32 s19, s27, s1
	global_load_dwordx2 v[158:159], v113, s[18:19]
	s_waitcnt vmcnt(17)
.LBB0_2278:
	v_sub_f32_e32 v83, v83, v124
	v_sub_f32_e32 v82, v82, v124
	v_sub_f32_e32 v81, v81, v124
	v_sub_f32_e32 v80, v80, v124
	v_pk_mul_f32 v[80:81], v[124:125], v[80:81] op_sel:[1,0]
	v_pk_mul_f32 v[82:83], v[124:125], v[82:83] op_sel:[1,0]
	v_sub_f32_e32 v43, v43, v124
	v_sub_f32_e32 v42, v42, v124
	v_sub_f32_e32 v41, v41, v124
	v_sub_f32_e32 v40, v40, v124
	v_pk_fma_f32 v[74:75], v[74:75], v[82:83], v[78:79]
	v_pk_fma_f32 v[72:73], v[72:73], v[80:81], v[76:77]
	v_pk_mul_f32 v[78:79], v[122:123], v[84:85] op_sel_hi:[0,1]
	v_pk_mul_f32 v[40:41], v[124:125], v[40:41] op_sel:[1,0]
	v_pk_mul_f32 v[42:43], v[124:125], v[42:43] op_sel:[1,0]
	v_pk_mul_f32 v[76:77], v[122:123], v[86:87] op_sel_hi:[0,1]
	v_pk_fma_f32 v[78:79], v[72:73], s[14:15], v[78:79] op_sel_hi:[1,0,1]
	v_pk_fma_f32 v[34:35], v[34:35], v[42:43], v[38:39]
	v_pk_fma_f32 v[32:33], v[32:33], v[40:41], v[36:37]
	v_pk_mul_f32 v[38:39], v[122:123], v[44:45] op_sel_hi:[0,1]
	v_pk_fma_f32 v[72:73], v[74:75], s[14:15], v[76:77] op_sel_hi:[1,0,1]
	v_pk_fma_f32 v[74:75], v[122:123], v[96:97], v[78:79] op_sel:[1,0,0]
	v_sub_f32_e32 v79, v101, v124
	v_sub_f32_e32 v78, v100, v124
	v_sub_f32_e32 v63, v63, v124
	v_sub_f32_e32 v62, v62, v124
	v_sub_f32_e32 v61, v61, v124
	v_sub_f32_e32 v60, v60, v124
	v_pk_mul_f32 v[36:37], v[122:123], v[46:47] op_sel_hi:[0,1]
	v_pk_fma_f32 v[32:33], v[32:33], s[14:15], v[38:39] op_sel_hi:[1,0,1]
	v_sub_f32_e32 v77, v103, v124
	v_sub_f32_e32 v76, v102, v124
	v_pk_mul_f32 v[60:61], v[124:125], v[60:61] op_sel:[1,0]
	v_pk_mul_f32 v[62:63], v[124:125], v[62:63] op_sel:[1,0]
	v_pk_fma_f32 v[34:35], v[34:35], s[14:15], v[36:37] op_sel_hi:[1,0,1]
	v_pk_fma_f32 v[38:39], v[122:123], v[48:49], v[32:33] op_sel:[1,0,0]
	v_pk_mul_f32 v[32:33], v[124:125], v[78:79] op_sel:[1,0]
	v_pk_fma_f32 v[54:55], v[54:55], v[62:63], v[58:59]
	v_pk_fma_f32 v[52:53], v[52:53], v[60:61], v[56:57]
	v_pk_mul_f32 v[56:57], v[122:123], v[66:67] op_sel_hi:[0,1]
	v_pk_mul_f32 v[58:59], v[122:123], v[64:65] op_sel_hi:[0,1]
	v_pk_fma_f32 v[36:37], v[122:123], v[50:51], v[34:35] op_sel:[1,0,0]
	v_pk_mul_f32 v[34:35], v[124:125], v[76:77] op_sel:[1,0]
	v_pk_fma_f32 v[32:33], v[88:89], v[32:33], v[92:93]
	v_pk_mul_f32 v[42:43], v[122:123], v[104:105] op_sel_hi:[0,1]
	v_pk_fma_f32 v[58:59], v[52:53], s[14:15], v[58:59] op_sel_hi:[1,0,1]
	v_pk_fma_f32 v[52:53], v[54:55], s[14:15], v[56:57] op_sel_hi:[1,0,1]
	v_pk_fma_f32 v[34:35], v[90:91], v[34:35], v[94:95]
	v_pk_mul_f32 v[40:41], v[122:123], v[106:107] op_sel_hi:[0,1]
	v_pk_fma_f32 v[42:43], v[32:33], s[14:15], v[42:43] op_sel_hi:[1,0,1]
	v_pk_fma_f32 v[52:53], v[122:123], v[70:71], v[52:53] op_sel:[1,0,0]
	v_pk_fma_f32 v[54:55], v[122:123], v[68:69], v[58:59] op_sel:[1,0,0]
	v_pk_fma_f32 v[32:33], v[34:35], s[14:15], v[40:41] op_sel_hi:[1,0,1]
	v_pk_fma_f32 v[34:35], v[122:123], v[108:109], v[42:43] op_sel:[1,0,0]
	v_pk_mov_b32 v[40:41], v[38:39], v[36:37] op_sel:[1,0]
	v_mov_b32_e32 v42, v38
; __device__ __forceinline__ float shx(float v, int o) { const int l = lane_now(); return __int_as_float(__builtin_amdgcn_ds_bpermute((l ^ o) << 2, __float_as_int(v))); }
; __device__ __forceinline__ unsigned pk2(float lo, float hi) { return f2bf(lo) | (f2bf(hi) << 16); }
; __device__ __forceinline__ float wave_sum(float v) {
; #pragma unroll
;     for (int o = 1; o < 64; o <<= 1) v += shx(v, o);
;     return v;
; template <int SRC, int EXTRA, bool OUT8 = false> ...
;     ...
;         float s = 0.f;
; #pragma unroll
;         for (int j = 0; j < 4; ++j) s += (v[j].x + v[j].y) + (v[j].z + v[j].w);
;         const float mean = wave_sum(s) * (1.f / 1024.f); float s2 = 0.f;
; #pragma unroll
;         for (int j = 0; j < 4; ++j) { v[j] = v[j] - mean; s2 += (v[j].x * v[j].x + v[j].y * v[j].y) + (v[j].z * v[j].z + v[j].w * v[j].w); }
;         const float rstd = 1.f / sqrtf(wave_sum(s2) * (1.f / 1024.f) + LN_EPS);
;         if (stats && lane == 0) { stats[2 * row] = mean; stats[2 * row + 1] = rstd; }
; #pragma unroll
;         for (int j = 0; j < 4; ++j) { v[j] = v[j] * rstd * gv[j] + bv[j]; if (of32) *(f32x4*)(of32 + (size_t)row * 1024 + 256 * j + 4 * lane) = v[j];
;             if (obf) { if constexpr (OUT8) { int w = 0; w = __builtin_amdgcn_cvt_pk_fp8_f32(v[j].x, v[j].y, w, false); w = __builtin_amdgcn_cvt_pk_fp8_f32(v[j].z, v[j].w, w, true); *(unsigned*)((unsigned char*)obf + (size_t)row * 1024 + 256 * j + 4 * lane) = (unsigned)w; }
;                 else { v2u o; o.x = pk2(v[j].x, v[j].y); o.y = pk2(v[j].z, v[j].w); *(v2u*)(obf + (size_t)row * 1024 + 256 * j + 4 * lane) = o; } } }
	v_mov_b32_e32 v43, v37
	v_pk_add_f32 v[40:41], v[40:41], v[42:43]
	v_pk_mov_b32 v[42:43], v[54:55], v[52:53] op_sel:[1,0]
	v_mov_b32_e32 v44, v54
	v_mov_b32_e32 v45, v53
	v_pk_add_f32 v[42:43], v[42:43], v[44:45]
	v_pk_fma_f32 v[72:73], v[122:123], v[98:99], v[72:73] op_sel:[1,0,0]
	v_pk_fma_f32 v[32:33], v[122:123], v[110:111], v[32:33] op_sel:[1,0,0]
	v_add_f32_e32 v40, v40, v41
	v_pk_add_f32 v[42:43], v[42:43], v[42:43] op_sel:[0,1] op_sel_hi:[1,0]
	v_add_f32_e32 v40, 0, v40
	v_add_f32_e32 v44, v74, v75
	v_add_f32_e32 v46, v72, v73
	v_mov_b32_e32 v41, v34
	v_mov_b32_e32 v43, v35
	v_mov_b32_e32 v45, v32
	v_mov_b32_e32 v47, v33
	v_pk_add_f32 v[40:41], v[40:41], v[42:43]
	v_pk_add_f32 v[42:43], v[44:45], v[46:47]
	s_andn2_b64 vcc, exec, s[4:5]
	v_pk_add_f32 v[40:41], v[40:41], v[42:43]
	s_nop 0
	v_add_f32_e32 v40, v40, v41
	s_nop 0
	s_nop 1
	v_mov_b32_dpp v41, v40 quad_perm:[1,0,3,2] row_mask:0xf bank_mask:0xf
	v_add_f32_e32 v40, v40, v41
	s_nop 0
	s_nop 1
	v_mov_b32_dpp v41, v40 quad_perm:[2,3,0,1] row_mask:0xf bank_mask:0xf
	v_add_f32_e32 v40, v40, v41
	s_nop 0
	s_nop 1
	v_mov_b32_dpp v41, v40 row_shl:4 row_mask:0xf bank_mask:0x5
	v_mov_b32_dpp v41, v40 row_shr:4 row_mask:0xf bank_mask:0xa
	v_add_f32_e32 v40, v40, v41
	s_nop 0
	s_nop 1
	v_mov_b32_dpp v41, v40 row_ror:8 row_mask:0xf bank_mask:0xf
	v_add_f32_e32 v40, v40, v41
	s_nop 0
	v_mov_b32_e32 v41, v40
	v_mov_b32_e32 v200, v40
	s_nop 1
	v_permlane16_swap_b32_e32 v41, v200
	v_cndmask_b32_e64 v41, v200, v41, s[98:99]
	v_add_f32_e32 v40, v40, v41
	s_nop 0
	v_mov_b32_e32 v41, v40
	v_mov_b32_e32 v200, v40
	s_nop 1
	v_permlane32_swap_b32_e32 v41, v200
	v_cndmask_b32_e64 v41, v200, v41, s[100:101]
	v_add_f32_e32 v40, v40, v41
	v_fmamk_f32 v37, v40, 0xba800000, v37
	v_fmamk_f32 v39, v40, 0xba800000, v39
	v_fmac_f32_e32 v36, 0xba800000, v40
	v_fmac_f32_e32 v38, 0xba800000, v40
	v_mul_f32_e32 v41, v39, v39
	v_mul_f32_e32 v42, v37, v37
	v_fmac_f32_e32 v41, v38, v38
	v_fmac_f32_e32 v42, v36, v36
	v_fmamk_f32 v53, v40, 0xba800000, v53
	v_fmamk_f32 v55, v40, 0xba800000, v55
	v_add_f32_e32 v41, v41, v42
	v_fmac_f32_e32 v52, 0xba800000, v40
	v_fmac_f32_e32 v54, 0xba800000, v40
	v_mul_f32_e32 v42, v55, v55
	v_mul_f32_e32 v43, v53, v53
	v_fmac_f32_e32 v42, v54, v54
	v_fmac_f32_e32 v43, v52, v52
	v_add_f32_e32 v42, v42, v43
	v_fmamk_f32 v73, v40, 0xba800000, v73
	v_fmamk_f32 v75, v40, 0xba800000, v75
	v_add_f32_e32 v41, v41, v42
	v_fmac_f32_e32 v72, 0xba800000, v40
	v_fmac_f32_e32 v74, 0xba800000, v40
	v_mul_f32_e32 v42, v75, v75
	v_mul_f32_e32 v43, v73, v73
	v_fmac_f32_e32 v42, v74, v74
	v_fmac_f32_e32 v43, v72, v72
	v_add_f32_e32 v42, v42, v43
	v_fmamk_f32 v33, v40, 0xba800000, v33
	v_fmamk_f32 v35, v40, 0xba800000, v35
	v_add_f32_e32 v41, v42, v41
	v_fmac_f32_e32 v32, 0xba800000, v40
	v_fmac_f32_e32 v34, 0xba800000, v40
	v_mul_f32_e32 v40, v35, v35
	v_mul_f32_e32 v42, v33, v33
	v_fmac_f32_e32 v40, v34, v34
	v_fmac_f32_e32 v42, v32, v32
	v_add_f32_e32 v40, v40, v42
	v_add_f32_e32 v40, v40, v41
	s_nop 0
	s_nop 1
	v_mov_b32_dpp v41, v40 quad_perm:[1,0,3,2] row_mask:0xf bank_mask:0xf
	v_add_f32_e32 v40, v40, v41
	s_nop 0
	s_nop 1
	v_mov_b32_dpp v41, v40 quad_perm:[2,3,0,1] row_mask:0xf bank_mask:0xf
	v_add_f32_e32 v40, v40, v41
	s_nop 0
	s_nop 1
	v_mov_b32_dpp v41, v40 row_shl:4 row_mask:0xf bank_mask:0x5
	v_mov_b32_dpp v41, v40 row_shr:4 row_mask:0xf bank_mask:0xa
	v_add_f32_e32 v40, v40, v41
	s_nop 0
	s_nop 1
	v_mov_b32_dpp v41, v40 row_ror:8 row_mask:0xf bank_mask:0xf
	v_add_f32_e32 v40, v40, v41
	s_nop 0
	v_mov_b32_e32 v41, v40
	v_mov_b32_e32 v200, v40
	s_nop 1
	v_permlane16_swap_b32_e32 v41, v200
	v_cndmask_b32_e64 v41, v200, v41, s[98:99]
	v_add_f32_e32 v40, v40, v41
	s_nop 0
	v_mov_b32_e32 v41, v40
	v_mov_b32_e32 v200, v40
	s_nop 1
	v_permlane32_swap_b32_e32 v41, v200
	v_cndmask_b32_e64 v41, v200, v41, s[100:101]
	s_cbranch_vccnz .LBB0_2245
	v_add_f32_e32 v40, v40, v41
	v_fmamk_f32 v40, v40, 0x3a800000, v126
	v_mul_f32_e32 v41, 0x4f800000, v40
	v_cmp_gt_f32_e32 vcc, s33, v40
	s_nop 1
	v_cndmask_b32_e32 v40, v40, v41, vcc
	v_sqrt_f32_e32 v41, v40
	s_nop 0
	v_add_u32_e32 v42, -1, v41
	v_fma_f32 v44, -v42, v41, v40
	v_add_u32_e32 v43, 1, v41
	v_cmp_ge_f32_e64 s[0:1], 0, v44
	s_nop 1
	v_cndmask_b32_e64 v42, v41, v42, s[0:1]
	v_fma_f32 v41, -v43, v41, v40
	v_cmp_lt_f32_e64 s[0:1], 0, v41
	s_nop 1
	v_cndmask_b32_e64 v41, v42, v43, s[0:1]
	v_mul_f32_e32 v42, 0x37800000, v41
	v_cndmask_b32_e32 v41, v41, v42, vcc
	v_cmp_class_f32_e32 vcc, v40, v127
	s_nop 1
	v_cndmask_b32_e32 v42, v41, v40, vcc
	v_div_scale_f32 v43, s[0:1], v42, v42, 1.0
	v_rcp_f32_e32 v44, v43
	v_lshl_add_u64 v[40:41], s[12:13], 0, v[112:113]
	v_fma_f32 v45, -v43, v44, 1.0
	v_fmac_f32_e32 v44, v45, v44
	v_div_scale_f32 v45, vcc, 1.0, v42, 1.0
	v_mul_f32_e32 v46, v45, v44
	v_fma_f32 v47, -v43, v46, v45
	v_fmac_f32_e32 v46, v47, v44
	v_fma_f32 v43, -v43, v46, v45
	v_div_fmas_f32 v43, v43, v44, v46
	v_div_fixup_f32 v42, v43, v42, 1.0
	v_pk_mul_f32 v[44:45], v[38:39], v[42:43] op_sel_hi:[1,0]
	v_pk_mul_f32 v[36:37], v[36:37], v[42:43] op_sel_hi:[1,0]
	v_pk_mul_f32 v[32:33], v[32:33], v[42:43] op_sel_hi:[1,0]
	v_pk_fma_f32 v[38:39], v[2:3], v[36:37], v[6:7]
	v_pk_fma_f32 v[36:37], v[0:1], v[44:45], v[4:5]
	global_store_dwordx4 v[40:41], v[36:39], off
	s_nop 1
	v_pk_mul_f32 v[36:37], v[54:55], v[42:43] op_sel_hi:[1,0]
	v_pk_mul_f32 v[38:39], v[52:53], v[42:43] op_sel_hi:[1,0]
	v_pk_fma_f32 v[36:37], v[8:9], v[36:37], v[16:17]
	v_pk_fma_f32 v[38:39], v[10:11], v[38:39], v[18:19]
	global_store_dwordx4 v[40:41], v[36:39], off offset:1024
	s_nop 1
	v_pk_mul_f32 v[36:37], v[74:75], v[42:43] op_sel_hi:[1,0]
	v_pk_mul_f32 v[38:39], v[72:73], v[42:43] op_sel_hi:[1,0]
	v_pk_fma_f32 v[36:37], v[12:13], v[36:37], v[20:21]
	v_pk_fma_f32 v[38:39], v[14:15], v[38:39], v[22:23]
	global_store_dwordx4 v[40:41], v[36:39], off offset:2048
	s_nop 1
	v_pk_mul_f32 v[36:37], v[34:35], v[42:43] op_sel_hi:[1,0]
	v_pk_fma_f32 v[34:35], v[26:27], v[32:33], v[30:31]
	v_pk_fma_f32 v[32:33], v[24:25], v[36:37], v[28:29]
	global_store_dwordx4 v[40:41], v[32:35], off offset:3072
	s_branch .LBB0_2245
